# GEMM tile end: leading half runs its epilogue before (not after) its align barrier, overlapping the trailing half's last MFMA block (up-proj and in/out/down-proj instances)
# speedup vs baseline: 1.0077x; 1.0077x over previous
.LBB0_39:
	s_mov_b32 s98, 1
	s_lshl_b32 s6, s62, 8
	s_ashr_i32 s7, s6, 31
	s_lshl_b64 s[6:7], s[6:7], 14
	s_add_u32 s8, s20, s6
	s_addc_u32 s9, s21, s7
	s_lshl_b32 s6, s59, 8
	v_max_f32_e32 v122, 0, v122
	v_mov_b32_e32 v0, v145
	s_ashr_i32 s7, s6, 31
	v_mul_f32_e32 v147, v122, v122
	v_max_f32_e32 v123, 0, v123
	v_max_f32_e32 v124, 0, v124
	s_lshl_b64 s[6:7], s[6:7], 1
	v_and_or_b32 v142, v0, 15, s38
	v_max_f32_e32 v122, 0, v127
	v_mul_f32_e32 v127, v123, v123
	v_max_f32_e32 v123, v128, v128
	v_mul_f32_e32 v128, v124, v124
	s_add_u32 s6, s8, s6
	v_lshlrev_b32_e32 v142, 14, v142
	v_and_b32_e32 v0, -16, v0
	v_max_f32_e32 v126, 0, v126
	v_mul_f32_e32 v122, v122, v122
	v_max_f32_e32 v123, 0, v123
	v_max_f32_e32 v124, 0, v129
	v_max_f32_e32 v125, 0, v125
	s_addc_u32 s7, s9, s7
	v_add3_u32 v0, v0, s57, v142
	v_mul_f32_e32 v126, v126, v126
	v_mul_f32_e32 v123, v123, v123
	v_mul_f32_e32 v124, v124, v124
	v_mul_f32_e32 v125, v125, v125
	v_cvt_pk_bf16_f32 v122, v126, v122
	v_max_f32_e32 v114, 0, v114
	v_max_f32_e32 v115, 0, v115
	v_max_f32_e32 v116, 0, v116
	v_cvt_pk_bf16_f32 v123, v123, v124
	v_cvt_pk_bf16_f32 v124, v147, v127
	v_cvt_pk_bf16_f32 v125, v128, v125
	global_store_dwordx4 v0, v[122:125], s[6:7]
	s_nop 1
	v_mul_f32_e32 v122, v114, v114
	v_max_f32_e32 v114, v119, v119
	v_mul_f32_e32 v119, v115, v115
	v_max_f32_e32 v115, v120, v120
	v_mul_f32_e32 v120, v116, v116
	v_max_f32_e32 v114, 0, v114
	v_max_f32_e32 v115, 0, v115
	v_max_f32_e32 v116, 0, v121
	v_max_f32_e32 v117, 0, v117
	v_max_f32_e32 v118, 0, v118
	v_mul_f32_e32 v114, v114, v114
	v_mul_f32_e32 v115, v115, v115
	v_mul_f32_e32 v116, v116, v116
	v_mul_f32_e32 v117, v117, v117
	v_max_f32_e32 v106, 0, v106
	v_lshl_add_u64 v[142:143], s[6:7], 0, v[0:1]
	v_mul_f32_e32 v118, v118, v118
	v_cvt_pk_bf16_f32 v114, v118, v114
	v_cvt_pk_bf16_f32 v115, v115, v116
	v_cvt_pk_bf16_f32 v116, v122, v119
	v_cvt_pk_bf16_f32 v117, v120, v117
	global_store_dwordx4 v0, v[114:117], s[6:7] offset:256
	s_nop 1
	v_max_f32_e32 v0, v110, v110
	v_mul_f32_e32 v110, v106, v106
	v_max_f32_e32 v107, 0, v107
	v_max_f32_e32 v108, 0, v108
	v_max_f32_e32 v0, 0, v0
	v_max_f32_e32 v106, 0, v111
	v_mul_f32_e32 v111, v107, v107
	v_max_f32_e32 v107, v112, v112
	v_mul_f32_e32 v112, v108, v108
	v_mul_f32_e32 v0, v0, v0
	v_mul_f32_e32 v106, v106, v106
	v_max_f32_e32 v107, 0, v107
	v_max_f32_e32 v108, 0, v113
	v_max_f32_e32 v98, 0, v98
	v_mul_f32_e32 v107, v107, v107
	v_mul_f32_e32 v108, v108, v108
	v_cvt_pk_bf16_f32 v106, v0, v106
	s_mov_b32 s6, 0x40000
	v_max_f32_e32 v0, v102, v102
	v_mul_f32_e32 v102, v98, v98
	v_max_f32_e32 v109, 0, v109
	v_cvt_pk_bf16_f32 v107, v107, v108
	v_cvt_pk_bf16_f32 v108, v110, v111
	v_add_co_u32_e32 v110, vcc, s6, v142
	v_max_f32_e32 v0, 0, v0
	v_max_f32_e32 v98, 0, v103
	v_mul_f32_e32 v109, v109, v109
	v_addc_co_u32_e32 v111, vcc, 0, v143, vcc
	v_mul_f32_e32 v0, v0, v0
	v_max_f32_e32 v99, 0, v99
	v_mul_f32_e32 v98, v98, v98
	v_max_f32_e32 v100, 0, v100
	v_max_f32_e32 v90, 0, v90
	v_cvt_pk_bf16_f32 v109, v112, v109
	global_store_dwordx4 v[110:111], v[106:109], off
	s_nop 1
	v_mul_f32_e32 v103, v99, v99
	v_max_f32_e32 v99, v104, v104
	v_mul_f32_e32 v104, v100, v100
	v_cvt_pk_bf16_f32 v98, v0, v98
	v_max_f32_e32 v0, v94, v94
	v_mul_f32_e32 v94, v90, v90
	v_max_f32_e32 v91, 0, v91
	v_max_f32_e32 v92, 0, v92
	v_max_f32_e32 v99, 0, v99
	v_max_f32_e32 v100, 0, v105
	v_max_f32_e32 v101, 0, v101
	v_max_f32_e32 v0, 0, v0
	v_max_f32_e32 v90, 0, v95
	v_mul_f32_e32 v95, v91, v91
	v_max_f32_e32 v91, v96, v96
	v_mul_f32_e32 v96, v92, v92
	v_mul_f32_e32 v99, v99, v99
	v_mul_f32_e32 v100, v100, v100
	v_mul_f32_e32 v101, v101, v101
	v_mul_f32_e32 v0, v0, v0
	v_mul_f32_e32 v90, v90, v90
	v_max_f32_e32 v91, 0, v91
	v_max_f32_e32 v92, 0, v97
	v_max_f32_e32 v82, 0, v82
	v_cvt_pk_bf16_f32 v99, v99, v100
	v_cvt_pk_bf16_f32 v100, v102, v103
	v_cvt_pk_bf16_f32 v101, v104, v101
	global_store_dwordx4 v[110:111], v[98:101], off offset:256
	s_nop 1
	v_mul_f32_e32 v91, v91, v91
	v_mul_f32_e32 v92, v92, v92
	v_cvt_pk_bf16_f32 v90, v0, v90
	s_mov_b32 s6, 0x80000
	v_max_f32_e32 v0, v86, v86
	v_mul_f32_e32 v86, v82, v82
	v_max_f32_e32 v93, 0, v93
	v_cvt_pk_bf16_f32 v91, v91, v92
	v_cvt_pk_bf16_f32 v92, v94, v95
	v_add_co_u32_e32 v94, vcc, s6, v142
	v_max_f32_e32 v0, 0, v0
	v_max_f32_e32 v82, 0, v87
	v_mul_f32_e32 v93, v93, v93
	v_addc_co_u32_e32 v95, vcc, 0, v143, vcc
	v_mul_f32_e32 v0, v0, v0
	v_max_f32_e32 v83, 0, v83
	v_mul_f32_e32 v82, v82, v82
	v_max_f32_e32 v84, 0, v84
	v_max_f32_e32 v74, 0, v74
	v_cvt_pk_bf16_f32 v93, v96, v93
	global_store_dwordx4 v[94:95], v[90:93], off
	s_nop 1
	v_mul_f32_e32 v87, v83, v83
	v_max_f32_e32 v83, v88, v88
	v_mul_f32_e32 v88, v84, v84
	v_cvt_pk_bf16_f32 v82, v0, v82
	v_max_f32_e32 v0, v78, v78
	v_mul_f32_e32 v78, v74, v74
	v_max_f32_e32 v75, 0, v75
	v_max_f32_e32 v76, 0, v76
	v_max_f32_e32 v83, 0, v83
	v_max_f32_e32 v84, 0, v89
	v_max_f32_e32 v85, 0, v85
	v_max_f32_e32 v0, 0, v0
	v_max_f32_e32 v74, 0, v79
	v_mul_f32_e32 v79, v75, v75
	v_max_f32_e32 v75, v80, v80
	v_mul_f32_e32 v80, v76, v76
	v_mul_f32_e32 v83, v83, v83
	v_mul_f32_e32 v84, v84, v84
	v_mul_f32_e32 v85, v85, v85
	v_mul_f32_e32 v0, v0, v0
	v_mul_f32_e32 v74, v74, v74
	v_max_f32_e32 v75, 0, v75
	v_max_f32_e32 v76, 0, v81
	v_max_f32_e32 v66, 0, v66
	v_cvt_pk_bf16_f32 v83, v83, v84
	v_cvt_pk_bf16_f32 v84, v86, v87
	v_cvt_pk_bf16_f32 v85, v88, v85
	global_store_dwordx4 v[94:95], v[82:85], off offset:256
	s_nop 1
	v_mul_f32_e32 v75, v75, v75
	v_mul_f32_e32 v76, v76, v76
	v_cvt_pk_bf16_f32 v74, v0, v74
	s_mov_b32 s6, 0xc0000
	v_max_f32_e32 v0, v70, v70
	v_mul_f32_e32 v70, v66, v66
	v_max_f32_e32 v77, 0, v77
	v_cvt_pk_bf16_f32 v75, v75, v76
	v_cvt_pk_bf16_f32 v76, v78, v79
	v_add_co_u32_e32 v78, vcc, s6, v142
	v_max_f32_e32 v0, 0, v0
	v_max_f32_e32 v66, 0, v71
	v_mul_f32_e32 v77, v77, v77
	v_addc_co_u32_e32 v79, vcc, 0, v143, vcc
	v_mul_f32_e32 v0, v0, v0
	v_max_f32_e32 v67, 0, v67
	v_mul_f32_e32 v66, v66, v66
	v_max_f32_e32 v68, 0, v68
	v_max_f32_e32 v58, 0, v58
	v_cvt_pk_bf16_f32 v77, v80, v77
	global_store_dwordx4 v[78:79], v[74:77], off
	s_nop 1
	v_mul_f32_e32 v71, v67, v67
	v_max_f32_e32 v67, v72, v72
	v_mul_f32_e32 v72, v68, v68
	v_cvt_pk_bf16_f32 v66, v0, v66
	v_max_f32_e32 v0, v62, v62
	v_mul_f32_e32 v62, v58, v58
	v_max_f32_e32 v59, 0, v59
	v_max_f32_e32 v60, 0, v60
	v_max_f32_e32 v67, 0, v67
	v_max_f32_e32 v68, 0, v73
	v_max_f32_e32 v69, 0, v69
	v_max_f32_e32 v0, 0, v0
	v_max_f32_e32 v58, 0, v63
	v_mul_f32_e32 v63, v59, v59
	v_max_f32_e32 v59, v64, v64
	v_mul_f32_e32 v64, v60, v60
	v_mul_f32_e32 v67, v67, v67
	v_mul_f32_e32 v68, v68, v68
	v_mul_f32_e32 v69, v69, v69
	v_mul_f32_e32 v0, v0, v0
	v_mul_f32_e32 v58, v58, v58
	v_max_f32_e32 v59, 0, v59
	v_max_f32_e32 v60, 0, v65
	v_max_f32_e32 v50, 0, v50
	v_cvt_pk_bf16_f32 v67, v67, v68
	v_cvt_pk_bf16_f32 v68, v70, v71
	v_cvt_pk_bf16_f32 v69, v72, v69
	global_store_dwordx4 v[78:79], v[66:69], off offset:256
	s_nop 1
	v_mul_f32_e32 v59, v59, v59
	v_mul_f32_e32 v60, v60, v60
	v_cvt_pk_bf16_f32 v58, v0, v58
	s_mov_b32 s6, 0x200000
	v_max_f32_e32 v0, v54, v54
	v_mul_f32_e32 v54, v50, v50
	v_max_f32_e32 v61, 0, v61
	v_cvt_pk_bf16_f32 v59, v59, v60
	v_cvt_pk_bf16_f32 v60, v62, v63
	v_add_co_u32_e32 v62, vcc, s6, v142
	v_max_f32_e32 v0, 0, v0
	v_max_f32_e32 v50, 0, v55
	v_mul_f32_e32 v61, v61, v61
	v_addc_co_u32_e32 v63, vcc, 0, v143, vcc
	v_mul_f32_e32 v0, v0, v0
	v_max_f32_e32 v51, 0, v51
	v_mul_f32_e32 v50, v50, v50
	v_max_f32_e32 v52, 0, v52
	v_max_f32_e32 v42, 0, v42
	v_cvt_pk_bf16_f32 v61, v64, v61
	global_store_dwordx4 v[62:63], v[58:61], off
	s_nop 1
	v_mul_f32_e32 v55, v51, v51
	v_max_f32_e32 v51, v56, v56
	v_mul_f32_e32 v56, v52, v52
	v_cvt_pk_bf16_f32 v50, v0, v50
	v_max_f32_e32 v0, v46, v46
	v_mul_f32_e32 v46, v42, v42
	v_max_f32_e32 v43, 0, v43
	v_max_f32_e32 v44, 0, v44
	v_max_f32_e32 v51, 0, v51
	v_max_f32_e32 v52, 0, v57
	v_max_f32_e32 v53, 0, v53
	v_max_f32_e32 v0, 0, v0
	v_max_f32_e32 v42, 0, v47
	v_mul_f32_e32 v47, v43, v43
	v_max_f32_e32 v43, v48, v48
	v_mul_f32_e32 v48, v44, v44
	v_mul_f32_e32 v51, v51, v51
	v_mul_f32_e32 v52, v52, v52
	v_mul_f32_e32 v53, v53, v53
	v_mul_f32_e32 v0, v0, v0
	v_mul_f32_e32 v42, v42, v42
	v_max_f32_e32 v43, 0, v43
	v_max_f32_e32 v44, 0, v49
	v_max_f32_e32 v34, 0, v34
	v_cvt_pk_bf16_f32 v51, v51, v52
	v_cvt_pk_bf16_f32 v52, v54, v55
	v_cvt_pk_bf16_f32 v53, v56, v53
	global_store_dwordx4 v[62:63], v[50:53], off offset:256
	s_nop 1
	v_mul_f32_e32 v43, v43, v43
	v_mul_f32_e32 v44, v44, v44
	v_cvt_pk_bf16_f32 v42, v0, v42
	s_mov_b32 s6, 0x240000
	v_max_f32_e32 v0, v38, v38
	v_mul_f32_e32 v38, v34, v34
	v_max_f32_e32 v45, 0, v45
	v_cvt_pk_bf16_f32 v43, v43, v44
	v_cvt_pk_bf16_f32 v44, v46, v47
	v_add_co_u32_e32 v46, vcc, s6, v142
	v_max_f32_e32 v0, 0, v0
	v_max_f32_e32 v34, 0, v39
	v_mul_f32_e32 v45, v45, v45
	v_addc_co_u32_e32 v47, vcc, 0, v143, vcc
	v_mul_f32_e32 v0, v0, v0
	v_max_f32_e32 v35, 0, v35
	v_mul_f32_e32 v34, v34, v34
	v_max_f32_e32 v36, 0, v36
	v_max_f32_e32 v26, 0, v26
	v_cvt_pk_bf16_f32 v45, v48, v45
	global_store_dwordx4 v[46:47], v[42:45], off
	s_nop 1
	v_mul_f32_e32 v39, v35, v35
	v_max_f32_e32 v35, v40, v40
	v_mul_f32_e32 v40, v36, v36
	v_cvt_pk_bf16_f32 v34, v0, v34
	v_max_f32_e32 v0, v30, v30
	v_mul_f32_e32 v30, v26, v26
	v_max_f32_e32 v27, 0, v27
	v_max_f32_e32 v28, 0, v28
	v_max_f32_e32 v35, 0, v35
	v_max_f32_e32 v36, 0, v41
	v_max_f32_e32 v37, 0, v37
	v_max_f32_e32 v0, 0, v0
	v_max_f32_e32 v26, 0, v31
	v_mul_f32_e32 v31, v27, v27
	v_max_f32_e32 v27, v32, v32
	v_mul_f32_e32 v32, v28, v28
	v_mul_f32_e32 v35, v35, v35
	v_mul_f32_e32 v36, v36, v36
	v_mul_f32_e32 v37, v37, v37
	v_mul_f32_e32 v0, v0, v0
	v_mul_f32_e32 v26, v26, v26
	v_max_f32_e32 v27, 0, v27
	v_max_f32_e32 v28, 0, v33
	v_max_f32_e32 v18, 0, v18
	v_cvt_pk_bf16_f32 v35, v35, v36
	v_cvt_pk_bf16_f32 v36, v38, v39
	v_cvt_pk_bf16_f32 v37, v40, v37
	global_store_dwordx4 v[46:47], v[34:37], off offset:256
	s_nop 1
	v_mul_f32_e32 v27, v27, v27
	v_mul_f32_e32 v28, v28, v28
	v_cvt_pk_bf16_f32 v26, v0, v26
	s_mov_b32 s6, 0x280000
	v_max_f32_e32 v0, v22, v22
	v_mul_f32_e32 v22, v18, v18
	v_max_f32_e32 v29, 0, v29
	v_cvt_pk_bf16_f32 v27, v27, v28
	v_cvt_pk_bf16_f32 v28, v30, v31
	v_add_co_u32_e32 v30, vcc, s6, v142
	v_max_f32_e32 v0, 0, v0
	v_max_f32_e32 v18, 0, v23
	v_mul_f32_e32 v29, v29, v29
	v_addc_co_u32_e32 v31, vcc, 0, v143, vcc
	v_mul_f32_e32 v0, v0, v0
	v_max_f32_e32 v19, 0, v19
	v_mul_f32_e32 v18, v18, v18
	v_max_f32_e32 v20, 0, v20
	v_max_f32_e32 v10, 0, v10
	v_max_f32_e32 v11, 0, v11
	v_max_f32_e32 v12, 0, v12
	v_cvt_pk_bf16_f32 v29, v32, v29
	global_store_dwordx4 v[30:31], v[26:29], off
	s_nop 1
	v_mul_f32_e32 v23, v19, v19
	v_max_f32_e32 v19, v24, v24
	v_mul_f32_e32 v24, v20, v20
	v_cvt_pk_bf16_f32 v18, v0, v18
	v_max_f32_e32 v0, v14, v14
	v_mul_f32_e32 v14, v10, v10
	v_max_f32_e32 v10, v15, v15
	v_mul_f32_e32 v15, v11, v11
	v_max_f32_e32 v11, v16, v16
	v_mul_f32_e32 v16, v12, v12
	v_max_f32_e32 v19, 0, v19
	v_max_f32_e32 v20, 0, v25
	v_max_f32_e32 v21, 0, v21
	v_max_f32_e32 v0, 0, v0
	v_max_f32_e32 v10, 0, v10
	v_max_f32_e32 v11, 0, v11
	v_max_f32_e32 v12, 0, v17
	v_mul_f32_e32 v19, v19, v19
	v_mul_f32_e32 v20, v20, v20
	v_mul_f32_e32 v21, v21, v21
	v_mul_f32_e32 v0, v0, v0
	v_mul_f32_e32 v10, v10, v10
	v_mul_f32_e32 v11, v11, v11
	v_mul_f32_e32 v12, v12, v12
	s_mov_b32 s6, 0x2c0000
	v_max_f32_e32 v2, 0, v2
	v_max_f32_e32 v3, 0, v3
	v_max_f32_e32 v4, 0, v4
	v_cvt_pk_bf16_f32 v19, v19, v20
	v_cvt_pk_bf16_f32 v20, v22, v23
	v_cvt_pk_bf16_f32 v21, v24, v21
	global_store_dwordx4 v[30:31], v[18:21], off offset:256
	s_nop 1
	v_cvt_pk_bf16_f32 v10, v0, v10
	v_cvt_pk_bf16_f32 v11, v11, v12
	v_cvt_pk_bf16_f32 v12, v14, v15
	v_add_co_u32_e32 v14, vcc, s6, v142
	v_max_f32_e32 v0, v6, v6
	v_mul_f32_e32 v6, v2, v2
	v_max_f32_e32 v2, v7, v7
	v_mul_f32_e32 v7, v3, v3
	v_max_f32_e32 v3, v8, v8
	v_mul_f32_e32 v8, v4, v4
	v_max_f32_e32 v13, 0, v13
	v_addc_co_u32_e32 v15, vcc, 0, v143, vcc
	v_max_f32_e32 v2, 0, v2
	v_max_f32_e32 v3, 0, v3
	v_max_f32_e32 v4, 0, v9
	v_max_f32_e32 v5, 0, v5
	v_mul_f32_e32 v13, v13, v13
	v_max_f32_e32 v0, 0, v0
	v_mul_f32_e32 v2, v2, v2
	v_mul_f32_e32 v3, v3, v3
	v_mul_f32_e32 v4, v4, v4
	v_mul_f32_e32 v5, v5, v5
	s_andn2_b64 vcc, exec, s[40:41]
	s_mov_b64 s[6:7], -1
	s_mov_b32 s70, 0x2aaaaaab
	s_mov_b64 s[72:73], 0x26000
	v_cvt_pk_bf16_f32 v13, v16, v13
	global_store_dwordx4 v[14:15], v[10:13], off
	s_nop 1
	v_mul_f32_e32 v0, v0, v0
	v_cvt_pk_bf16_f32 v2, v0, v2
	v_cvt_pk_bf16_f32 v3, v3, v4
	v_cvt_pk_bf16_f32 v4, v6, v7
	v_cvt_pk_bf16_f32 v5, v8, v5
	global_store_dwordx4 v[14:15], v[2:5], off offset:256
	s_nop 1
	s_cmp_lg_u64 s[28:29], 0
	s_cbranch_scc1 .Lalign1_skip
	s_barrier
.Lalign1_skip:
	s_cbranch_vccnz .LBB0_28
	s_andn2_b64 vcc, exec, s[28:29]
	s_cbranch_vccnz .LBB0_27
	s_barrier
	s_branch .LBB0_27

.LBB0_353:
	s_mov_b32 s98, 1
	s_lshl_b32 s8, s84, 8
	s_mul_hi_i32 s9, s8, s14
	s_mul_i32 s8, s8, s14
	s_lshl_b64 s[8:9], s[8:9], 1
	s_add_u32 s10, s46, s8
	v_mov_b32_e32 v0, v143
	s_addc_u32 s11, s47, s9
	s_lshl_b32 s8, s87, 8
	s_ashr_i32 s9, s8, 31
	v_lshlrev_b32_e32 v145, 1, v0
	s_lshl_b64 s[8:9], s[8:9], 1
	v_and_or_b32 v145, v145, 30, s78
	s_add_u32 s8, s10, s8
	v_mul_lo_u32 v145, v145, s14
	v_and_b32_e32 v0, -16, v0
	s_addc_u32 s9, s11, s9
	v_add3_u32 v0, v0, s73, v145
	v_lshl_add_u64 v[146:147], s[8:9], 0, v[0:1]
	v_cvt_pk_bf16_f32 v126, v126, v127
	v_cvt_pk_bf16_f32 v127, v128, v129
	v_cvt_pk_bf16_f32 v128, v122, v123
	v_cvt_pk_bf16_f32 v129, v124, v125
	global_store_dwordx4 v0, v[126:129], s[8:9]
	v_cvt_pk_bf16_f32 v114, v114, v115
	v_cvt_pk_bf16_f32 v115, v116, v117
	v_cvt_pk_bf16_f32 v116, v106, v107
	v_cvt_pk_bf16_f32 v117, v108, v109
	global_store_dwordx4 v0, v[114:117], s[8:9] offset:256
	v_cvt_pk_bf16_f32 v106, v118, v119
	v_cvt_pk_bf16_f32 v107, v120, v121
	v_cvt_pk_bf16_f32 v108, v110, v111
	v_lshl_add_u64 v[110:111], v[146:147], 0, s[58:59]
	v_cvt_pk_bf16_f32 v109, v112, v113
	global_store_dwordx4 v[110:111], v[106:109], off
	v_cvt_pk_bf16_f32 v98, v98, v99
	v_cvt_pk_bf16_f32 v99, v100, v101
	v_cvt_pk_bf16_f32 v100, v90, v91
	v_cvt_pk_bf16_f32 v101, v92, v93
	global_store_dwordx4 v[110:111], v[98:101], off offset:256
	v_cvt_pk_bf16_f32 v90, v102, v103
	v_cvt_pk_bf16_f32 v91, v104, v105
	v_cvt_pk_bf16_f32 v92, v94, v95
	v_lshl_add_u64 v[94:95], v[110:111], 0, s[58:59]
	v_cvt_pk_bf16_f32 v93, v96, v97
	global_store_dwordx4 v[94:95], v[90:93], off
	v_cvt_pk_bf16_f32 v82, v82, v83
	v_cvt_pk_bf16_f32 v83, v84, v85
	v_cvt_pk_bf16_f32 v84, v74, v75
	v_cvt_pk_bf16_f32 v85, v76, v77
	global_store_dwordx4 v[94:95], v[82:85], off offset:256
	v_cvt_pk_bf16_f32 v74, v86, v87
	v_cvt_pk_bf16_f32 v75, v88, v89
	v_cvt_pk_bf16_f32 v76, v78, v79
	v_lshl_add_u64 v[78:79], v[94:95], 0, s[58:59]
	v_cvt_pk_bf16_f32 v77, v80, v81
	global_store_dwordx4 v[78:79], v[74:77], off
	v_cvt_pk_bf16_f32 v70, v70, v71
	v_cvt_pk_bf16_f32 v71, v72, v73
	v_cvt_pk_bf16_f32 v72, v66, v67
	v_cvt_pk_bf16_f32 v73, v68, v69
	global_store_dwordx4 v[78:79], v[70:73], off offset:256
	v_cvt_pk_bf16_f32 v62, v62, v63
	v_cvt_pk_bf16_f32 v63, v64, v65
	v_cvt_pk_bf16_f32 v64, v58, v59
	v_lshl_add_u64 v[58:59], v[78:79], 0, s[64:65]
	v_cvt_pk_bf16_f32 v65, v60, v61
	global_store_dwordx4 v[58:59], v[62:65], off
	v_cvt_pk_bf16_f32 v50, v50, v51
	v_cvt_pk_bf16_f32 v51, v52, v53
	v_cvt_pk_bf16_f32 v52, v42, v43
	v_cvt_pk_bf16_f32 v53, v44, v45
	global_store_dwordx4 v[58:59], v[50:53], off offset:256
	v_cvt_pk_bf16_f32 v42, v54, v55
	v_cvt_pk_bf16_f32 v43, v56, v57
	v_cvt_pk_bf16_f32 v44, v46, v47
	v_lshl_add_u64 v[46:47], v[58:59], 0, s[58:59]
	v_cvt_pk_bf16_f32 v45, v48, v49
	global_store_dwordx4 v[46:47], v[42:45], off
	v_cvt_pk_bf16_f32 v34, v34, v35
	v_cvt_pk_bf16_f32 v35, v36, v37
	v_cvt_pk_bf16_f32 v36, v26, v27
	v_cvt_pk_bf16_f32 v37, v28, v29
	global_store_dwordx4 v[46:47], v[34:37], off offset:256
	v_cvt_pk_bf16_f32 v26, v38, v39
	v_cvt_pk_bf16_f32 v27, v40, v41
	v_cvt_pk_bf16_f32 v28, v30, v31
	v_lshl_add_u64 v[30:31], v[46:47], 0, s[58:59]
	v_cvt_pk_bf16_f32 v29, v32, v33
	global_store_dwordx4 v[30:31], v[26:29], off
	v_cvt_pk_bf16_f32 v18, v18, v19
	v_cvt_pk_bf16_f32 v19, v20, v21
	v_cvt_pk_bf16_f32 v20, v10, v11
	v_cvt_pk_bf16_f32 v21, v12, v13
	global_store_dwordx4 v[30:31], v[18:21], off offset:256
	v_cvt_pk_bf16_f32 v10, v22, v23
	v_cvt_pk_bf16_f32 v11, v24, v25
	v_cvt_pk_bf16_f32 v12, v14, v15
	v_lshl_add_u64 v[14:15], v[30:31], 0, s[58:59]
	s_and_b64 vcc, exec, s[40:41]
	s_mov_b64 s[8:9], -1
	v_cvt_pk_bf16_f32 v13, v16, v17
	global_store_dwordx4 v[14:15], v[10:13], off
	v_cvt_pk_bf16_f32 v6, v6, v7
	v_cvt_pk_bf16_f32 v7, v8, v9
	v_cvt_pk_bf16_f32 v8, v2, v3
	v_cvt_pk_bf16_f32 v9, v4, v5
	global_store_dwordx4 v[14:15], v[6:9], off offset:256
	s_cmp_lg_u64 s[56:57], 0
	s_cbranch_scc1 .Lalign3_skip
	s_barrier
.Lalign3_skip:
	s_cbranch_vccnz .LBB0_342
	s_andn2_b64 vcc, exec, s[56:57]
	s_cbranch_vccnz .LBB0_341
	s_barrier
	s_branch .LBB0_341
